# E27: non-fused attention unit: LDS fragment reads of the QK^T/PV MFMA ladders renamed into a rotating pool of dead VGPR quads and issued 6 groups ahead, lgkmcnt waits regenerated (on top of v21)
# speedup vs baseline: 1.0032x; 1.0001x over previous
.LBB0_426:
	ds_read_b128 v[194:197], v158
	ds_read_b128 v[202:205], v159
	ds_read_b128 v[206:209], v160
	ds_read_b128 v[212:215], v161
	ds_read_b128 v[216:219], v158 offset:4096
	ds_read_b128 v[220:223], v159 offset:4096
	s_nop 0
	s_nop 0
	s_lshl_b32 s20, s67, 7
	s_lshr_b32 s29, s33, s63
	s_cmp_eq_u32 s67, 0
	v_add_u32_e32 v133, s20, v136
	s_cselect_b64 s[34:35], -1, 0
	s_addk_i32 s20, 0xc0
	s_cmp_gt_i32 s20, s29
	s_nop 0
	ds_read_b128 v[224:227], v160 offset:4096
	s_waitcnt lgkmcnt(6)
	v_mfma_f32_16x16x32_bf16 v[100:103], v[194:197], v[96:99], 0
	s_cselect_b64 s[20:21], -1, 0
	s_or_b64 s[20:21], s[34:35], s[20:21]
	s_andn2_b64 vcc, exec, s[20:21]
	s_nop 0
	ds_read_b128 v[228:231], v161 offset:4096
	s_waitcnt lgkmcnt(6)
	v_mfma_f32_16x16x32_bf16 v[100:103], v[202:205], v[92:95], v[100:103]
	s_nop 0
	s_nop 0
	s_nop 0
	ds_read_b128 v[232:235], v158 offset:8192
	s_waitcnt lgkmcnt(6)
	v_mfma_f32_16x16x32_bf16 v[100:103], v[206:209], v[88:91], v[100:103]
	s_nop 0
	s_nop 0
	ds_read_b128 v[236:239], v159 offset:8192
	s_waitcnt lgkmcnt(6)
	v_mfma_f32_16x16x32_bf16 v[128:131], v[212:215], v[84:87], v[100:103]
	s_nop 4
	s_nop 0
	s_nop 0
	s_nop 0
	ds_read_b128 v[246:249], v160 offset:8192
	s_waitcnt lgkmcnt(6)
	v_mfma_f32_16x16x32_bf16 v[100:103], v[216:219], v[96:99], 0
	s_nop 0
	ds_read_b128 v[250:253], v161 offset:8192
	s_waitcnt lgkmcnt(6)
	v_mfma_f32_16x16x32_bf16 v[100:103], v[220:223], v[92:95], v[100:103]
	s_nop 0
	s_nop 0
	ds_read_b128 v[194:197], v158 offset:12288
	s_waitcnt lgkmcnt(6)
	v_mfma_f32_16x16x32_bf16 v[100:103], v[224:227], v[88:91], v[100:103]
	s_nop 0
	s_nop 0
	ds_read_b128 v[202:205], v159 offset:12288
	s_waitcnt lgkmcnt(6)
	v_mfma_f32_16x16x32_bf16 v[124:127], v[228:231], v[84:87], v[100:103]
	s_nop 4
	s_nop 0
	s_nop 0
	s_nop 0
	ds_read_b128 v[206:209], v160 offset:12288
	s_waitcnt lgkmcnt(6)
	v_mfma_f32_16x16x32_bf16 v[100:103], v[232:235], v[96:99], 0
	s_nop 0
	ds_read_b128 v[212:215], v161 offset:12288
	s_waitcnt lgkmcnt(6)
	v_mfma_f32_16x16x32_bf16 v[100:103], v[236:239], v[92:95], v[100:103]
	s_nop 0
	s_nop 0
	ds_read_b128 v[216:219], v158 offset:16384
	s_waitcnt lgkmcnt(6)
	v_mfma_f32_16x16x32_bf16 v[100:103], v[246:249], v[88:91], v[100:103]
	s_nop 0
	s_nop 0
	ds_read_b128 v[220:223], v159 offset:16384
	s_waitcnt lgkmcnt(6)
	v_mfma_f32_16x16x32_bf16 v[120:123], v[250:253], v[84:87], v[100:103]
	s_nop 4
	s_nop 0
	s_nop 0
	s_nop 0
	ds_read_b128 v[224:227], v160 offset:16384
	s_waitcnt lgkmcnt(6)
	v_mfma_f32_16x16x32_bf16 v[100:103], v[194:197], v[96:99], 0
	s_nop 0
	ds_read_b128 v[228:231], v161 offset:16384
	s_waitcnt lgkmcnt(6)
	v_mfma_f32_16x16x32_bf16 v[100:103], v[202:205], v[92:95], v[100:103]
	s_nop 0
	s_nop 0
	ds_read_b128 v[232:235], v158 offset:20480
	s_waitcnt lgkmcnt(6)
	v_mfma_f32_16x16x32_bf16 v[100:103], v[206:209], v[88:91], v[100:103]
	s_nop 0
	s_nop 0
	ds_read_b128 v[236:239], v159 offset:20480
	s_waitcnt lgkmcnt(6)
	v_mfma_f32_16x16x32_bf16 v[116:119], v[212:215], v[84:87], v[100:103]
	s_nop 4
	s_nop 0
	s_nop 0
	s_nop 0
	ds_read_b128 v[246:249], v160 offset:20480
	s_waitcnt lgkmcnt(6)
	v_mfma_f32_16x16x32_bf16 v[100:103], v[216:219], v[96:99], 0
	s_nop 0
	ds_read_b128 v[250:253], v161 offset:20480
	s_waitcnt lgkmcnt(6)
	v_mfma_f32_16x16x32_bf16 v[100:103], v[220:223], v[92:95], v[100:103]
	s_nop 0
	s_nop 0
	ds_read_b128 v[194:197], v158 offset:24576
	s_waitcnt lgkmcnt(6)
	v_mfma_f32_16x16x32_bf16 v[100:103], v[224:227], v[88:91], v[100:103]
	s_nop 0
	s_nop 0
	ds_read_b128 v[202:205], v159 offset:24576
	s_waitcnt lgkmcnt(6)
	v_mfma_f32_16x16x32_bf16 v[112:115], v[228:231], v[84:87], v[100:103]
	s_nop 4
	s_nop 0
	s_nop 0
	s_nop 0
	ds_read_b128 v[206:209], v160 offset:24576
	s_waitcnt lgkmcnt(6)
	v_mfma_f32_16x16x32_bf16 v[100:103], v[232:235], v[96:99], 0
	s_nop 0
	ds_read_b128 v[212:215], v161 offset:24576
	s_waitcnt lgkmcnt(6)
	v_mfma_f32_16x16x32_bf16 v[100:103], v[236:239], v[92:95], v[100:103]
	s_nop 0
	s_nop 0
	ds_read_b128 v[216:219], v158 offset:28672
	s_waitcnt lgkmcnt(6)
	v_mfma_f32_16x16x32_bf16 v[100:103], v[246:249], v[88:91], v[100:103]
	s_nop 0
	s_nop 0
	ds_read_b128 v[220:223], v159 offset:28672
	s_waitcnt lgkmcnt(6)
	v_mfma_f32_16x16x32_bf16 v[108:111], v[250:253], v[84:87], v[100:103]
	s_nop 4
	s_nop 0
	s_nop 0
	s_nop 0
	ds_read_b128 v[224:227], v160 offset:28672
	s_waitcnt lgkmcnt(6)
	v_mfma_f32_16x16x32_bf16 v[100:103], v[194:197], v[96:99], 0
	s_nop 0
	ds_read_b128 v[228:231], v161 offset:28672
	s_waitcnt lgkmcnt(6)
	v_mfma_f32_16x16x32_bf16 v[100:103], v[202:205], v[92:95], v[100:103]
	s_nop 0
	s_nop 0
	ds_read_b128 v[232:235], v158 offset:32768
	s_waitcnt lgkmcnt(6)
	v_mfma_f32_16x16x32_bf16 v[100:103], v[206:209], v[88:91], v[100:103]
	s_nop 0
	s_nop 0
	ds_read_b128 v[236:239], v159 offset:32768
	s_waitcnt lgkmcnt(6)
	v_mfma_f32_16x16x32_bf16 v[104:107], v[212:215], v[84:87], v[100:103]
	s_nop 4
	s_nop 0
	s_nop 0
	ds_read_b128 v[246:249], v160 offset:32768
	s_waitcnt lgkmcnt(6)
	v_mfma_f32_16x16x32_bf16 v[100:103], v[216:219], v[96:99], 0
	ds_read_b128 v[250:253], v161 offset:32768
	s_waitcnt lgkmcnt(6)
	v_mfma_f32_16x16x32_bf16 v[100:103], v[220:223], v[92:95], v[100:103]
	s_nop 0
	s_nop 0
	ds_read_b64_tr_b16 v[196:197], v163
	ds_read_b64_tr_b16 v[194:195], v162
	s_waitcnt lgkmcnt(7)
	v_mfma_f32_16x16x32_bf16 v[100:103], v[224:227], v[88:91], v[100:103]
	s_nop 0
	s_nop 0
	ds_read_b64_tr_b16 v[202:203], v162 offset:8192
	ds_read_b64_tr_b16 v[204:205], v164
	s_waitcnt lgkmcnt(8)
	v_mfma_f32_16x16x32_bf16 v[100:103], v[228:231], v[84:87], v[100:103]
	s_nop 0
	s_nop 0
	ds_read_b64_tr_b16 v[206:207], v162 offset:16384
	ds_read_b64_tr_b16 v[208:209], v165
	s_waitcnt lgkmcnt(9)
	v_mfma_f32_16x16x32_bf16 v[96:99], v[232:235], v[96:99], 0
	s_nop 0
	s_nop 0
	ds_read_b64_tr_b16 v[212:213], v162 offset:24576
	ds_read_b64_tr_b16 v[214:215], v166
	s_waitcnt lgkmcnt(10)
	v_mfma_f32_16x16x32_bf16 v[92:95], v[236:239], v[92:95], v[96:99]
	s_nop 4
	s_nop 0
	s_nop 0
	ds_read_b64_tr_b16 v[218:219], v163 offset:8
	ds_read_b64_tr_b16 v[216:217], v162 offset:8
	s_waitcnt lgkmcnt(11)
	v_mfma_f32_16x16x32_bf16 v[88:91], v[246:249], v[88:91], v[92:95]
	s_nop 2
	s_nop 0
	s_nop 0
	ds_read_b64_tr_b16 v[220:221], v162 offset:32768
	ds_read_b64_tr_b16 v[222:223], v167
	s_waitcnt lgkmcnt(12)
	v_mfma_f32_16x16x32_bf16 v[92:95], v[250:253], v[84:87], v[88:91]
	v_mov_b32_e32 v84, s89
	s_nop 1
	v_cndmask_b32_e64 v90, v128, v84, s[6:7]
	v_cndmask_b32_e64 v91, v129, v211, s[10:11]
	s_nop 2
	v_cndmask_b32_e64 v84, v92, v211, s[8:9]
	v_cndmask_b32_e64 v84, v84, v92, s[6:7]
	v_cndmask_b32_e64 v85, v211, v93, s[6:7]
	v_cndmask_b32_e64 v88, v130, v211, s[12:13]
	v_cndmask_b32_e64 v89, v131, v211, s[14:15]
	v_cndmask_b32_e64 v87, v93, v85, s[18:19]
	v_cndmask_b32_e64 v86, v92, v84, s[18:19]
	v_cndmask_b32_e64 v85, v95, v211, s[16:17]
	v_cndmask_b32_e64 v84, v94, v211, s[18:19]
	s_cbranch_vccnz .LBB0_428
	v_add_u32_e32 v93, v133, v150
	v_cmp_lt_i32_e32 vcc, 63, v133
	v_cmp_gt_i32_e64 s[20:21], s29, v93
	v_mov_b32_e32 v92, s89
	s_and_b64 s[20:21], vcc, s[20:21]
	v_cndmask_b32_e64 v90, v92, v90, s[20:21]
	v_or_b32_e32 v92, 1, v93
	v_cmp_gt_i32_e64 s[20:21], s29, v92
	s_and_b64 s[20:21], vcc, s[20:21]
	v_or_b32_e32 v92, 2, v93
	v_cndmask_b32_e64 v91, v211, v91, s[20:21]
	v_cmp_gt_i32_e64 s[20:21], s29, v92
	s_and_b64 s[20:21], vcc, s[20:21]
	v_or_b32_e32 v92, 3, v93
	v_cndmask_b32_e64 v88, v211, v88, s[20:21]
	v_cmp_gt_i32_e64 s[20:21], s29, v92
	s_and_b64 vcc, vcc, s[20:21]
	v_add_u32_e32 v93, v133, v151
	v_cndmask_b32_e32 v89, v211, v89, vcc
	v_cmp_lt_i32_e32 vcc, 47, v133
	v_cmp_gt_i32_e64 s[20:21], s29, v93
	v_mov_b32_e32 v92, s89
	s_and_b64 s[20:21], vcc, s[20:21]
	v_cndmask_b32_e64 v124, v92, v124, s[20:21]
	v_or_b32_e32 v92, 1, v93
	v_cmp_gt_i32_e64 s[20:21], s29, v92
	s_and_b64 s[20:21], vcc, s[20:21]
	v_or_b32_e32 v92, 2, v93
	v_cndmask_b32_e64 v125, v211, v125, s[20:21]
	v_cmp_gt_i32_e64 s[20:21], s29, v92
	s_and_b64 s[20:21], vcc, s[20:21]
	v_or_b32_e32 v92, 3, v93
	v_cndmask_b32_e64 v126, v211, v126, s[20:21]
	v_cmp_gt_i32_e64 s[20:21], s29, v92
	s_and_b64 vcc, vcc, s[20:21]
	v_add_u32_e32 v93, v133, v152
	v_cndmask_b32_e32 v127, v211, v127, vcc
	v_cmp_lt_i32_e32 vcc, 31, v133
	v_cmp_gt_i32_e64 s[20:21], s29, v93
	v_mov_b32_e32 v92, s89
	s_and_b64 s[20:21], vcc, s[20:21]
	v_cndmask_b32_e64 v120, v92, v120, s[20:21]
	v_or_b32_e32 v92, 1, v93
	v_cmp_gt_i32_e64 s[20:21], s29, v92
	s_and_b64 s[20:21], vcc, s[20:21]
	v_or_b32_e32 v92, 2, v93
	v_cndmask_b32_e64 v121, v211, v121, s[20:21]
	v_cmp_gt_i32_e64 s[20:21], s29, v92
	s_and_b64 s[20:21], vcc, s[20:21]
	v_or_b32_e32 v92, 3, v93
	v_cndmask_b32_e64 v122, v211, v122, s[20:21]
	v_cmp_gt_i32_e64 s[20:21], s29, v92
	s_and_b64 vcc, vcc, s[20:21]
	v_add_u32_e32 v93, v133, v153
	v_cndmask_b32_e32 v123, v211, v123, vcc
	v_cmp_lt_i32_e32 vcc, 15, v133
	v_cmp_gt_i32_e64 s[20:21], s29, v93
	v_mov_b32_e32 v92, s89
	s_and_b64 s[20:21], vcc, s[20:21]
	v_cndmask_b32_e64 v116, v92, v116, s[20:21]
	v_or_b32_e32 v92, 1, v93
	v_cmp_gt_i32_e64 s[20:21], s29, v92
	s_and_b64 s[20:21], vcc, s[20:21]
	v_or_b32_e32 v92, 2, v93
	v_cndmask_b32_e64 v117, v211, v117, s[20:21]
	v_cmp_gt_i32_e64 s[20:21], s29, v92
	s_and_b64 s[20:21], vcc, s[20:21]
	v_or_b32_e32 v92, 3, v93
	v_cndmask_b32_e64 v118, v211, v118, s[20:21]
	v_cmp_gt_i32_e64 s[20:21], s29, v92
	s_and_b64 vcc, vcc, s[20:21]
	v_or_b32_e32 v93, v133, v139
	v_cndmask_b32_e32 v119, v211, v119, vcc
	v_cmp_lt_i32_e32 vcc, -1, v133
	v_cmp_gt_i32_e64 s[20:21], s29, v93
	v_mov_b32_e32 v92, s89
	s_and_b64 s[20:21], vcc, s[20:21]
	v_cndmask_b32_e64 v112, v92, v112, s[20:21]
	v_or_b32_e32 v92, 1, v93
	v_cmp_gt_i32_e64 s[20:21], s29, v92
	s_and_b64 s[20:21], vcc, s[20:21]
	v_or_b32_e32 v92, 2, v93
	v_cndmask_b32_e64 v113, v211, v113, s[20:21]
	v_cmp_gt_i32_e64 s[20:21], s29, v92
	s_and_b64 s[20:21], vcc, s[20:21]
	v_or_b32_e32 v92, 3, v93
	v_cndmask_b32_e64 v114, v211, v114, s[20:21]
	v_cmp_gt_i32_e64 s[20:21], s29, v92
	s_and_b64 vcc, vcc, s[20:21]
	v_add_u32_e32 v93, v133, v154
	s_movk_i32 s20, 0xffef
	v_cndmask_b32_e32 v115, v211, v115, vcc
	v_cmp_lt_i32_e32 vcc, s20, v133
	v_cmp_gt_i32_e64 s[20:21], s29, v93
	v_mov_b32_e32 v92, s89
	s_and_b64 s[20:21], vcc, s[20:21]
	v_cndmask_b32_e64 v108, v92, v108, s[20:21]
	v_or_b32_e32 v92, 1, v93
	v_cmp_gt_i32_e64 s[20:21], s29, v92
	s_and_b64 s[20:21], vcc, s[20:21]
	v_or_b32_e32 v92, 2, v93
	v_cndmask_b32_e64 v109, v211, v109, s[20:21]
	v_cmp_gt_i32_e64 s[20:21], s29, v92
	s_and_b64 s[20:21], vcc, s[20:21]
	v_or_b32_e32 v92, 3, v93
	v_cndmask_b32_e64 v110, v211, v110, s[20:21]
	v_cmp_gt_i32_e64 s[20:21], s29, v92
	s_and_b64 vcc, vcc, s[20:21]
	v_add_u32_e32 v93, v133, v155
	s_movk_i32 s20, 0xffdf
	v_cndmask_b32_e32 v111, v211, v111, vcc
	v_cmp_lt_i32_e32 vcc, s20, v133
	v_cmp_gt_i32_e64 s[20:21], s29, v93
	v_mov_b32_e32 v92, s89
	s_and_b64 s[20:21], vcc, s[20:21]
	v_cndmask_b32_e64 v104, v92, v104, s[20:21]
	v_or_b32_e32 v92, 1, v93
	v_cmp_gt_i32_e64 s[20:21], s29, v92
	s_and_b64 s[20:21], vcc, s[20:21]
	v_or_b32_e32 v92, 2, v93
	v_cndmask_b32_e64 v105, v211, v105, s[20:21]
	v_cmp_gt_i32_e64 s[20:21], s29, v92
	s_and_b64 s[20:21], vcc, s[20:21]
	v_or_b32_e32 v92, 3, v93
	v_cndmask_b32_e64 v106, v211, v106, s[20:21]
	v_cmp_gt_i32_e64 s[20:21], s29, v92
	s_and_b64 vcc, vcc, s[20:21]
	v_add_u32_e32 v93, v133, v156
	s_movk_i32 s20, 0xffcf
	v_cndmask_b32_e32 v107, v211, v107, vcc
	v_cmp_lt_i32_e32 vcc, s20, v133
	v_cmp_gt_i32_e64 s[20:21], s29, v93
	v_mov_b32_e32 v92, s89
	s_and_b64 s[20:21], vcc, s[20:21]
	v_cndmask_b32_e64 v100, v92, v100, s[20:21]
	v_or_b32_e32 v92, 1, v93
	v_cmp_gt_i32_e64 s[20:21], s29, v92
	s_and_b64 s[20:21], vcc, s[20:21]
	v_or_b32_e32 v92, 2, v93
	v_cndmask_b32_e64 v101, v211, v101, s[20:21]
	v_cmp_gt_i32_e64 s[20:21], s29, v92
	s_and_b64 s[20:21], vcc, s[20:21]
	v_or_b32_e32 v92, 3, v93
	v_cndmask_b32_e64 v102, v211, v102, s[20:21]
	v_cmp_gt_i32_e64 s[20:21], s29, v92
	s_and_b64 vcc, vcc, s[20:21]
	v_add_u32_e32 v93, v133, v157
	s_movk_i32 s20, 0xffbf
	v_cndmask_b32_e32 v103, v211, v103, vcc
	v_cmp_lt_i32_e32 vcc, s20, v133
	v_cmp_gt_i32_e64 s[20:21], s29, v93
	v_mov_b32_e32 v92, s89
	s_and_b64 s[20:21], vcc, s[20:21]
	v_cndmask_b32_e64 v86, v92, v86, s[20:21]
	v_or_b32_e32 v92, 1, v93
	v_cmp_gt_i32_e64 s[20:21], s29, v92
	s_and_b64 s[20:21], vcc, s[20:21]
	v_or_b32_e32 v92, 2, v93
	v_cndmask_b32_e64 v87, v211, v87, s[20:21]
	v_cmp_gt_i32_e64 s[20:21], s29, v92
	s_and_b64 s[20:21], vcc, s[20:21]
	v_or_b32_e32 v92, 3, v93
	v_cndmask_b32_e64 v84, v211, v84, s[20:21]
	v_cmp_gt_i32_e64 s[20:21], s29, v92
	s_and_b64 vcc, vcc, s[20:21]
	v_cndmask_b32_e32 v85, v211, v85, vcc
.LBB0_428:
	s_mov_b32 s20, 0xff61b1e6
	v_max3_f32 v92, v90, s20, v91
	v_max3_f32 v92, v92, v88, v89
	v_max3_f32 v92, v92, v124, v125
	v_max3_f32 v92, v92, v126, v127
	v_max3_f32 v92, v92, v120, v121
	v_max3_f32 v92, v92, v122, v123
	v_max3_f32 v92, v92, v116, v117
	v_max3_f32 v92, v92, v118, v119
	v_max3_f32 v92, v92, v112, v113
	v_max3_f32 v92, v92, v114, v115
	v_max3_f32 v92, v92, v108, v109
	v_max3_f32 v92, v92, v110, v111
	v_max3_f32 v92, v92, v104, v105
	v_max3_f32 v92, v92, v106, v107
	v_max3_f32 v92, v92, v100, v101
	v_max3_f32 v92, v92, v102, v103
	v_max3_f32 v92, v92, v86, v87
	v_max3_f32 v92, v92, v84, v85
	ds_bpermute_b32 v93, v140, v92
	s_mul_i32 s36, s61, 0xc00
	s_bfe_u32 s34, s31, 0x30003
	s_mov_b32 s31, s57
	s_ashr_i32 s37, s36, 31
	s_nop 0
	s_waitcnt lgkmcnt(0)
	v_max_f32_e32 v93, v93, v93
	v_max_f32_e32 v92, v92, v93
	ds_bpermute_b32 v93, v141, v92
	s_lshl_b64 s[20:21], s[30:31], s28
	s_lshl_b64 s[28:29], s[36:37], 1
	s_add_u32 s30, s50, s28
	s_addc_u32 s28, s51, s29
	s_nop 0
	s_waitcnt lgkmcnt(0)
	v_max_f32_e32 v93, v93, v93
	v_max_f32_e32 v128, v92, v93
	v_sub_f32_e32 v90, v90, v128
	v_sub_f32_e32 v91, v91, v128
	v_exp_f32_e32 v90, v90
	v_exp_f32_e32 v91, v91
	v_sub_f32_e32 v88, v88, v128
	v_exp_f32_e32 v88, v88
	v_sub_f32_e32 v89, v89, v128
	v_exp_f32_e32 v89, v89
	v_sub_f32_e32 v93, v124, v128
	v_add_f32_e32 v92, 0, v90
	v_exp_f32_e32 v94, v93
	v_sub_f32_e32 v93, v125, v128
	v_add_f32_e32 v92, v91, v92
	v_exp_f32_e32 v95, v93
	v_sub_f32_e32 v93, v126, v128
	v_add_f32_e32 v92, v88, v92
	v_exp_f32_e32 v96, v93
	v_sub_f32_e32 v93, v127, v128
	v_add_f32_e32 v92, v89, v92
	v_exp_f32_e32 v97, v93
	v_sub_f32_e32 v93, v120, v128
	v_add_f32_e32 v92, v94, v92
	v_exp_f32_e32 v98, v93
	v_sub_f32_e32 v93, v121, v128
	v_add_f32_e32 v92, v95, v92
	v_exp_f32_e32 v99, v93
	v_sub_f32_e32 v93, v122, v128
	v_add_f32_e32 v92, v96, v92
	v_exp_f32_e32 v120, v93
	v_sub_f32_e32 v93, v123, v128
	v_add_f32_e32 v92, v97, v92
	v_exp_f32_e32 v121, v93
	v_sub_f32_e32 v93, v116, v128
	v_add_f32_e32 v92, v98, v92
	v_exp_f32_e32 v116, v93
	v_sub_f32_e32 v93, v117, v128
	v_add_f32_e32 v92, v99, v92
	v_exp_f32_e32 v117, v93
	v_sub_f32_e32 v93, v118, v128
	v_add_f32_e32 v92, v120, v92
	v_exp_f32_e32 v118, v93
	v_sub_f32_e32 v93, v119, v128
	v_add_f32_e32 v92, v121, v92
	v_exp_f32_e32 v119, v93
	v_sub_f32_e32 v93, v112, v128
	v_add_f32_e32 v92, v116, v92
	v_exp_f32_e32 v112, v93
	v_sub_f32_e32 v93, v113, v128
	v_add_f32_e32 v92, v117, v92
	v_exp_f32_e32 v113, v93
	v_sub_f32_e32 v93, v114, v128
	v_add_f32_e32 v92, v118, v92
	v_exp_f32_e32 v114, v93
	v_sub_f32_e32 v93, v115, v128
	v_add_f32_e32 v92, v119, v92
	v_exp_f32_e32 v115, v93
	v_sub_f32_e32 v93, v108, v128
	v_add_f32_e32 v92, v112, v92
	v_exp_f32_e32 v108, v93
	v_sub_f32_e32 v93, v109, v128
	v_add_f32_e32 v92, v113, v92
	v_exp_f32_e32 v109, v93
	v_sub_f32_e32 v93, v110, v128
	v_add_f32_e32 v92, v114, v92
	v_exp_f32_e32 v110, v93
	v_sub_f32_e32 v93, v111, v128
	v_add_f32_e32 v92, v115, v92
	v_exp_f32_e32 v111, v93
	v_sub_f32_e32 v93, v104, v128
	v_add_f32_e32 v92, v108, v92
	v_exp_f32_e32 v104, v93
	v_sub_f32_e32 v93, v105, v128
	v_add_f32_e32 v92, v109, v92
	v_exp_f32_e32 v105, v93
	v_sub_f32_e32 v93, v106, v128
	v_add_f32_e32 v92, v110, v92
	v_exp_f32_e32 v106, v93
	v_sub_f32_e32 v93, v107, v128
	v_add_f32_e32 v92, v111, v92
	v_exp_f32_e32 v107, v93
	v_sub_f32_e32 v93, v100, v128
	v_add_f32_e32 v92, v104, v92
	v_exp_f32_e32 v122, v93
	v_sub_f32_e32 v93, v101, v128
	v_add_f32_e32 v92, v105, v92
	v_exp_f32_e32 v123, v93
	v_sub_f32_e32 v93, v102, v128
	v_add_f32_e32 v92, v106, v92
	v_exp_f32_e32 v124, v93
	v_sub_f32_e32 v93, v103, v128
	v_add_f32_e32 v92, v107, v92
	v_exp_f32_e32 v125, v93
	v_sub_f32_e32 v86, v86, v128
	v_add_f32_e32 v92, v122, v92
	v_exp_f32_e32 v86, v86
	v_sub_f32_e32 v87, v87, v128
	v_add_f32_e32 v92, v123, v92
	v_exp_f32_e32 v87, v87
	v_sub_f32_e32 v84, v84, v128
	v_add_f32_e32 v92, v124, v92
	v_exp_f32_e32 v126, v84
	v_sub_f32_e32 v84, v85, v128
	v_add_f32_e32 v92, v125, v92
	v_exp_f32_e32 v85, v84
	v_add_f32_e32 v84, v86, v92
	v_add_f32_e32 v84, v87, v84
	v_add_f32_e32 v84, v126, v84
	v_add_f32_e32 v127, v85, v84
	v_cvt_pk_bf16_f32 v92, v90, v91
	v_cvt_pk_bf16_f32 v93, v88, v89
	v_cvt_pk_bf16_f32 v94, v94, v95
	v_cvt_pk_bf16_f32 v95, v96, v97
	v_cvt_pk_bf16_f32 v96, v98, v99
	v_cvt_pk_bf16_f32 v97, v120, v121
	v_cvt_pk_bf16_f32 v98, v116, v117
	v_cvt_pk_bf16_f32 v99, v118, v119
	v_cvt_pk_bf16_f32 v100, v112, v113
	v_cvt_pk_bf16_f32 v101, v114, v115
	v_cvt_pk_bf16_f32 v102, v108, v109
	v_cvt_pk_bf16_f32 v103, v110, v111
	v_cvt_pk_bf16_f32 v88, v104, v105
	v_cvt_pk_bf16_f32 v89, v106, v107
	v_cvt_pk_bf16_f32 v90, v122, v123
	v_cvt_pk_bf16_f32 v91, v124, v125
	v_cvt_pk_bf16_f32 v84, v86, v87
	v_cvt_pk_bf16_f32 v85, v126, v85
	s_nop 0
	s_nop 0
	s_nop 0
	s_nop 0
	s_nop 0
	ds_read_b64_tr_b16 v[226:227], v164 offset:8
	ds_read_b64_tr_b16 v[224:225], v162 offset:8200
	v_mfma_f32_16x16x32_bf16 v[104:107], v[194:197], v[92:95], 0
	s_nop 0
	s_nop 0
	ds_bpermute_b32 v86, v140, v127
	s_add_u32 s20, s20, s66
	s_nop 0
	ds_read_b64_tr_b16 v[230:231], v165 offset:8
	ds_read_b64_tr_b16 v[228:229], v162 offset:16392
	v_mfma_f32_16x16x32_bf16 v[104:107], v[202:205], v[96:99], v[104:107]
	s_nop 0
	s_nop 0
	s_nop 0
	s_nop 0
	s_nop 0
	s_waitcnt lgkmcnt(2)
	v_add_f32_e32 v87, v127, v86
	ds_read_b64_tr_b16 v[234:235], v166 offset:8
	ds_read_b64_tr_b16 v[232:233], v162 offset:24584
	v_mfma_f32_16x16x32_bf16 v[104:107], v[206:209], v[100:103], v[104:107]
	ds_bpermute_b32 v112, v141, v87
	v_mov_b32_e32 v86, v201
	s_nop 0
	s_nop 0
	s_nop 0
	ds_read_b64_tr_b16 v[238:239], v167 offset:8
	ds_read_b64_tr_b16 v[236:237], v162 offset:32776
	v_mfma_f32_16x16x32_bf16 v[104:107], v[212:215], v[88:91], v[104:107]
	s_nop 0
	s_nop 0
	s_nop 0
	s_nop 0
	s_waitcnt lgkmcnt(2)
	v_add_f32_e32 v112, v87, v112
	v_mov_b32_e32 v87, v201
	s_nop 0
	ds_read_b64_tr_b16 v[248:249], v169
	ds_read_b64_tr_b16 v[246:247], v168
	v_mfma_f32_16x16x32_bf16 v[114:117], v[216:219], v[92:95], 0
	v_div_scale_f32 v113, s[36:37], v112, v112, 1.0
	v_rcp_f32_e32 v126, v113
	ds_read_b64_tr_b16 v[250:251], v168 offset:8192
	ds_read_b64_tr_b16 v[252:253], v170
	v_mfma_f32_16x16x32_bf16 v[118:121], v[220:223], v[84:87], v[104:107]
	v_div_scale_f32 v127, vcc, 1.0, v112, 1.0
	v_fma_f32 v110, -v113, v126, 1.0
	s_nop 0
	s_nop 0
	s_nop 0
	ds_read_b64_tr_b16 v[194:195], v168 offset:16384
	ds_read_b64_tr_b16 v[196:197], v171
	v_mfma_f32_16x16x32_bf16 v[104:107], v[224:227], v[96:99], v[114:117]
	s_nop 0
	s_nop 0
	v_fmac_f32_e32 v126, v110, v126
	s_nop 0
	s_nop 0
	ds_read_b64_tr_b16 v[202:203], v168 offset:24576
	ds_read_b64_tr_b16 v[204:205], v172
	v_mfma_f32_16x16x32_bf16 v[104:107], v[228:231], v[100:103], v[104:107]
	v_mul_f32_e32 v114, v127, v126
	v_fma_f32 v115, -v113, v114, v127
	v_fmac_f32_e32 v114, v115, v126
	s_nop 0
	ds_read_b64_tr_b16 v[206:207], v168 offset:32768
	ds_read_b64_tr_b16 v[208:209], v173
	v_mfma_f32_16x16x32_bf16 v[104:107], v[232:235], v[88:91], v[104:107]
	v_fma_f32 v113, -v113, v114, v127
	v_div_fmas_f32 v113, v113, v126, v114
	v_div_fixup_f32 v113, v113, v112, 1.0
	s_nop 0
	ds_read_b64_tr_b16 v[214:215], v169 offset:8
	ds_read_b64_tr_b16 v[212:213], v168 offset:8
	s_waitcnt lgkmcnt(12)
	v_mfma_f32_16x16x32_bf16 v[106:109], v[236:239], v[84:87], v[104:107]
	v_mul_f32_e32 v110, v121, v113
	s_addc_u32 s21, s21, 0
	s_lshl_b32 s29, s34, 8
	v_mul_f32_e32 v104, v118, v113
	v_mul_f32_e32 v105, v119, v113
	v_cvt_pk_bf16_f32 v104, v104, v105
	v_mul_f32_e32 v105, v120, v113
	s_nop 1
	v_mul_f32_e32 v106, v106, v113
	v_mul_f32_e32 v107, v107, v113
	v_cvt_pk_bf16_f32 v105, v105, v110
	v_cvt_pk_bf16_f32 v106, v106, v107
	v_mul_f32_e32 v107, v108, v113
	v_mul_f32_e32 v108, v109, v113
	v_cvt_pk_bf16_f32 v107, v107, v108
	s_nop 0
	s_nop 0
	s_nop 0
	s_nop 0
	s_nop 0
	ds_read_b64_tr_b16 v[218:219], v170 offset:8
	ds_read_b64_tr_b16 v[216:217], v168 offset:8200
	s_waitcnt lgkmcnt(12)
	v_mfma_f32_16x16x32_bf16 v[108:111], v[246:249], v[92:95], 0
	v_or_b32_e32 v118, v133, v134
	v_ashrrev_i32_e32 v119, 31, v118
	v_lshlrev_b64 v[126:127], s63, v[118:119]
	s_nop 0
	s_nop 0
	s_nop 0
	ds_read_b64_tr_b16 v[222:223], v171 offset:8
	ds_read_b64_tr_b16 v[220:221], v168 offset:16392
	s_waitcnt lgkmcnt(12)
	v_mfma_f32_16x16x32_bf16 v[108:111], v[250:253], v[96:99], v[108:111]
	s_nop 0
	s_nop 0
	s_nop 0
	s_nop 0
	s_add_u32 s30, s30, s29
	s_nop 0
	ds_read_b64_tr_b16 v[226:227], v172 offset:8
	ds_read_b64_tr_b16 v[224:225], v168 offset:24584
	s_waitcnt lgkmcnt(12)
	v_mfma_f32_16x16x32_bf16 v[108:111], v[194:197], v[100:103], v[108:111]
	s_nop 0
	s_nop 0
	s_addc_u32 s31, s28, 0
	v_mov_b32_e32 v133, v201
	s_nop 0
	ds_read_b64_tr_b16 v[230:231], v173 offset:8
	ds_read_b64_tr_b16 v[228:229], v168 offset:32776
	s_waitcnt lgkmcnt(12)
	v_mfma_f32_16x16x32_bf16 v[122:125], v[202:205], v[88:91], v[108:111]
	s_nop 2
	v_lshl_add_u64 v[108:109], s[20:21], 0, v[126:127]
	s_nop 0
	s_nop 0
	ds_read_b64_tr_b16 v[234:235], v175
	ds_read_b64_tr_b16 v[232:233], v174
	s_waitcnt lgkmcnt(12)
	v_mfma_f32_16x16x32_bf16 v[114:117], v[206:209], v[84:87], v[122:125]
	v_mov_b64_e32 v[110:111], s[30:31]
	v_mad_u64_u32 v[110:111], s[20:21], v108, s88, v[110:111]
	s_nop 0
	s_nop 0
	s_nop 0
	s_nop 0
	ds_read_b64_tr_b16 v[236:237], v174 offset:8192
	ds_read_b64_tr_b16 v[238:239], v176
	s_waitcnt lgkmcnt(12)
	v_mfma_f32_16x16x32_bf16 v[186:189], v[212:215], v[92:95], 0
	s_nop 0
	s_nop 0
	s_nop 0
	v_mov_b32_e32 v130, v111
	s_nop 0
	ds_read_b64_tr_b16 v[246:247], v174 offset:16384
	ds_read_b64_tr_b16 v[248:249], v177
	s_waitcnt lgkmcnt(12)
	v_mfma_f32_16x16x32_bf16 v[124:127], v[216:219], v[96:99], v[186:189]
	s_nop 2
	s_nop 0
	s_nop 0
	v_mul_f32_e32 v114, v114, v113
	v_mul_f32_e32 v115, v115, v113
	s_nop 0
	ds_read_b64_tr_b16 v[250:251], v174 offset:24576
	ds_read_b64_tr_b16 v[252:253], v178
	s_waitcnt lgkmcnt(12)
	v_mfma_f32_16x16x32_bf16 v[118:121], v[220:223], v[100:103], v[124:127]
	v_mad_u64_u32 v[122:123], s[20:21], v109, s88, v[130:131]
	v_mov_b32_e32 v111, v122
	s_nop 0
	ds_read_b64_tr_b16 v[194:195], v174 offset:32768
	ds_read_b64_tr_b16 v[196:197], v179
	s_waitcnt lgkmcnt(12)
	v_mfma_f32_16x16x32_bf16 v[118:121], v[224:227], v[88:91], v[118:121]
	v_lshl_add_u64 v[110:111], v[110:111], 0, v[132:133]
	global_store_dwordx4 v[110:111], v[104:107], off
	v_cvt_pk_bf16_f32 v114, v114, v115
	v_mul_f32_e32 v115, v116, v113
	v_mul_f32_e32 v116, v117, v113
	s_nop 0
	ds_read_b64_tr_b16 v[204:205], v175 offset:8
	ds_read_b64_tr_b16 v[202:203], v174 offset:8
	s_waitcnt lgkmcnt(12)
	v_mfma_f32_16x16x32_bf16 v[104:107], v[228:231], v[84:87], v[118:121]
	v_cvt_pk_bf16_f32 v115, v115, v116
	s_nop 7
	v_mul_f32_e32 v104, v113, v104
	v_mul_f32_e32 v105, v113, v105
	v_cvt_pk_bf16_f32 v116, v104, v105
	v_mul_f32_e32 v104, v113, v106
	v_mul_f32_e32 v105, v113, v107
	v_cvt_pk_bf16_f32 v117, v104, v105
	s_nop 0
	s_nop 0
	s_nop 0
	s_nop 0
	s_nop 0
	ds_read_b64_tr_b16 v[208:209], v176 offset:8
	ds_read_b64_tr_b16 v[206:207], v174 offset:8200
	s_waitcnt lgkmcnt(12)
	v_mfma_f32_16x16x32_bf16 v[104:107], v[232:235], v[92:95], 0
	s_nop 0
	ds_read_b64_tr_b16 v[214:215], v177 offset:8
	ds_read_b64_tr_b16 v[212:213], v174 offset:16392
	s_waitcnt lgkmcnt(12)
	v_mfma_f32_16x16x32_bf16 v[104:107], v[236:239], v[96:99], v[104:107]
	s_nop 0
	s_nop 0
	s_nop 0
	ds_read_b64_tr_b16 v[218:219], v178 offset:8
	ds_read_b64_tr_b16 v[216:217], v174 offset:24584
	s_waitcnt lgkmcnt(12)
	v_mfma_f32_16x16x32_bf16 v[104:107], v[246:249], v[100:103], v[104:107]
	s_nop 0
	s_nop 0
	s_nop 0
	ds_read_b64_tr_b16 v[222:223], v179 offset:8
	ds_read_b64_tr_b16 v[220:221], v174 offset:32776
	s_waitcnt lgkmcnt(12)
	v_mfma_f32_16x16x32_bf16 v[104:107], v[250:253], v[88:91], v[104:107]
	s_nop 0
	s_nop 0
	s_nop 0
	s_nop 0
	ds_read_b64_tr_b16 v[226:227], v181
	ds_read_b64_tr_b16 v[224:225], v180
	s_waitcnt lgkmcnt(12)
	v_mfma_f32_16x16x32_bf16 v[104:107], v[194:197], v[84:87], v[104:107]
	s_nop 0
	s_nop 0
	s_nop 0
	ds_read_b64_tr_b16 v[228:229], v180 offset:8192
	ds_read_b64_tr_b16 v[230:231], v182
	s_waitcnt lgkmcnt(12)
	v_mfma_f32_16x16x32_bf16 v[118:121], v[202:205], v[92:95], 0
	s_nop 0
	s_nop 0
	s_nop 1
	v_mul_f32_e32 v104, v113, v104
	v_mul_f32_e32 v105, v113, v105
	s_nop 0
	ds_read_b64_tr_b16 v[232:233], v180 offset:16384
	ds_read_b64_tr_b16 v[234:235], v183
	s_waitcnt lgkmcnt(12)
	v_mfma_f32_16x16x32_bf16 v[118:121], v[206:209], v[96:99], v[118:121]
	s_nop 0
	s_nop 0
	s_nop 0
	ds_read_b64_tr_b16 v[236:237], v180 offset:24576
	ds_read_b64_tr_b16 v[238:239], v184
	s_waitcnt lgkmcnt(12)
	v_mfma_f32_16x16x32_bf16 v[124:127], v[212:215], v[100:103], v[118:121]
	s_nop 3
	s_nop 0
	s_nop 0
	s_nop 0
	global_store_dwordx4 v[110:111], v[114:117], off offset:64
	s_nop 0
	ds_read_b64_tr_b16 v[246:247], v180 offset:32768
	ds_read_b64_tr_b16 v[248:249], v185
	s_waitcnt lgkmcnt(12)
	v_mfma_f32_16x16x32_bf16 v[118:121], v[216:219], v[88:91], v[124:127]
	v_cvt_pk_bf16_f32 v104, v104, v105
	v_mul_f32_e32 v105, v113, v106
	v_mul_f32_e32 v106, v113, v107
	s_nop 0
	ds_read_b64_tr_b16 v[252:253], v181 offset:8
	ds_read_b64_tr_b16 v[250:251], v180 offset:8
	s_waitcnt lgkmcnt(12)
	v_mfma_f32_16x16x32_bf16 v[114:117], v[220:223], v[84:87], v[118:121]
	v_cvt_pk_bf16_f32 v105, v105, v106
	s_nop 7
	v_mul_f32_e32 v106, v113, v114
	v_mul_f32_e32 v107, v113, v115
	v_cvt_pk_bf16_f32 v106, v106, v107
	v_mul_f32_e32 v107, v113, v116
	v_mul_f32_e32 v114, v113, v117
	v_cvt_pk_bf16_f32 v107, v107, v114
	s_nop 0
	s_nop 0
	s_nop 0
	s_nop 0
	s_nop 0
	ds_read_b64_tr_b16 v[196:197], v182 offset:8
	ds_read_b64_tr_b16 v[194:195], v180 offset:8200
	s_waitcnt lgkmcnt(12)
	v_mfma_f32_16x16x32_bf16 v[114:117], v[224:227], v[92:95], 0
	s_nop 0
	ds_read_b64_tr_b16 v[204:205], v183 offset:8
	ds_read_b64_tr_b16 v[202:203], v180 offset:16392
	s_waitcnt lgkmcnt(12)
	v_mfma_f32_16x16x32_bf16 v[114:117], v[228:231], v[96:99], v[114:117]
	s_nop 0
	s_nop 0
	s_nop 0
	ds_read_b64_tr_b16 v[208:209], v184 offset:8
	ds_read_b64_tr_b16 v[206:207], v180 offset:24584
	s_waitcnt lgkmcnt(12)
	v_mfma_f32_16x16x32_bf16 v[114:117], v[232:235], v[100:103], v[114:117]
	s_nop 0
	s_nop 0
	s_nop 0
	ds_read_b64_tr_b16 v[214:215], v185 offset:8
	ds_read_b64_tr_b16 v[212:213], v180 offset:32776
	s_waitcnt lgkmcnt(12)
	v_mfma_f32_16x16x32_bf16 v[114:117], v[236:239], v[88:91], v[114:117]
	s_nop 0
	s_nop 0
	s_nop 0
	s_nop 0
	s_waitcnt lgkmcnt(10)
	v_mfma_f32_16x16x32_bf16 v[114:117], v[246:249], v[84:87], v[114:117]
	s_nop 0
	s_nop 0
	s_nop 0
	s_waitcnt lgkmcnt(8)
	v_mfma_f32_16x16x32_bf16 v[92:95], v[250:253], v[92:95], 0
	s_nop 0
	s_nop 0
	s_nop 0
	s_waitcnt lgkmcnt(6)
	v_mfma_f32_16x16x32_bf16 v[92:95], v[194:197], v[96:99], v[92:95]
	s_nop 0
	s_nop 0
	s_nop 0
	s_waitcnt lgkmcnt(4)
	v_mfma_f32_16x16x32_bf16 v[98:101], v[202:205], v[100:103], v[92:95]
	s_nop 3
	s_nop 0
	s_nop 0
	global_store_dwordx4 v[110:111], v[104:107], off offset:128
	s_nop 0
	s_waitcnt lgkmcnt(2)
	v_mfma_f32_16x16x32_bf16 v[94:97], v[206:209], v[88:91], v[98:101]
	s_nop 0
	v_mul_f32_e32 v88, v113, v114
	v_mul_f32_e32 v89, v113, v115
	s_nop 0
	s_waitcnt lgkmcnt(0)
	v_mfma_f32_16x16x32_bf16 v[84:87], v[212:215], v[84:87], v[94:97]
	v_cvt_pk_bf16_f32 v88, v88, v89
	v_mul_f32_e32 v89, v113, v116
	v_mul_f32_e32 v90, v113, v117
	s_nop 5
	v_mul_f32_e32 v84, v113, v84
	v_mul_f32_e32 v85, v113, v85
	v_cvt_pk_bf16_f32 v89, v89, v90
	v_cvt_pk_bf16_f32 v90, v84, v85
	v_mul_f32_e32 v84, v113, v86
	v_mul_f32_e32 v85, v113, v87
	v_cvt_pk_bf16_f32 v91, v84, v85
	global_store_dwordx4 v[110:111], v[88:91], off offset:192
	s_and_saveexec_b64 s[20:21], s[4:5]
	s_cbranch_execz .LBB0_399
	v_log_f32_e32 v86, v112
	s_ashr_i32 s28, s61, 31
	v_mov_b32_e32 v84, s61
	v_mov_b32_e32 v85, s28
	v_add_f32_e32 v86, v128, v86
	v_mad_u64_u32 v[84:85], s[28:29], v108, 3, v[84:85]
	v_mul_f32_e32 v88, 0x3f317218, v86
	v_mov_b32_e32 v86, v85
	v_mad_u64_u32 v[86:87], s[28:29], v109, 3, v[86:87]
	v_mov_b32_e32 v85, v86
	v_lshlrev_b64 v[84:85], 5, v[84:85]
	v_lshl_add_u64 v[84:85], s[24:25], 0, v[84:85]
	s_lshl_b32 s56, s34, 2
	v_lshl_add_u64 v[84:85], v[84:85], 0, s[56:57]
	global_store_dword v[84:85], v88, off
	s_branch .LBB0_399
